# GLA chunk loop: loop-top wait ladder no longer waits for the previous chunk's stores
# baseline (speedup 1.0000x reference)
.LBB0_732:
	v_add_u32_e32 v32, v105, v59
	s_add_i32 s91, s91, 1
	s_waitcnt vmcnt(4)
	ds_write_b128 v63, v[16:19]
	s_waitcnt vmcnt(4)
	ds_write_b128 v103, v[20:23]
	s_waitcnt vmcnt(4)
	ds_write_b64 v104, v[70:71]
	s_waitcnt vmcnt(4)
	ds_write_b128 v32, v[24:27] offset:27648
	s_waitcnt vmcnt(4)
	ds_write_b128 v137, v[28:31] offset:27648
	s_mov_b64 s[80:81], -1
	s_cmp_lt_u32 s91, s95
	v_add_u32_e32 v32, s86, v62
	s_cbranch_scc1 .LBB0_734
	v_add_u32_e32 v33, s86, v62
	s_mov_b64 s[80:81], 0
